# v10 + static s_setprio 1 for waves 4-7 during attention
# baseline (speedup 1.0000x reference)
.LBB0_823:
	s_cmp_lt_i32 s28, 7
	s_cselect_b64 s[0:1], -1, 0
	s_and_b64 s[8:9], s[0:1], s[6:7]
	s_andn2_b64 vcc, exec, s[8:9]
	s_cbranch_vccnz .LBB0_909
	s_cmp_lt_u32 s76, 4
	s_cbranch_scc1 .Latt_prio_skip
	s_setprio 1
.Latt_prio_skip:
	v_readlane_b32 s1, v247, 0
	s_ashr_i32 s0, s1, 4
	s_bfe_u32 s6, s1, 0x30001
	s_lshl_b32 s1, s1, 2
	s_and_b32 s3, s1, 4
	s_ashr_i32 s1, s0, 31
	s_lshl_b64 s[4:5], s[0:1], 12
	s_lshl_b32 s74, s76, 5
	s_add_u32 s75, s4, s74
	s_addc_u32 s79, s5, 0
	s_mul_i32 s4, s6, 0xc0
	s_add_u32 s4, s26, s4
	s_addc_u32 s5, s27, 0
	s_add_u32 s81, s4, 0x35400000
	s_addc_u32 s82, s5, 0
	s_lshl_b64 s[4:5], s[0:1], 22
	s_lshl_b32 s7, s6, 13
	s_lshl_b32 s83, s76, 10
	s_add_u32 s4, s26, s4
	s_addc_u32 s5, s27, s5
	s_add_u32 s4, s4, s7
	s_addc_u32 s5, s5, 0
	s_add_u32 s7, s4, s83
	s_addc_u32 s10, s5, 0
	s_add_u32 s14, s7, 0x2d400000
	s_addc_u32 s15, s10, 0
	s_lshl_b64 s[0:1], s[0:1], 18
	s_add_u32 s0, s26, s0
	s_addc_u32 s1, s27, s1
	s_lshl_b32 s12, s64, 4
	s_and_b32 s84, s12, 0xc00
	s_add_u32 s0, s0, s84
	s_addc_u32 s1, s1, 0
	s_add_u32 s16, s0, 0x29000000
	s_addc_u32 s17, s1, 0
	s_and_b32 s12, s83, 0xfffff000
	s_add_u32 s4, s4, s12
	s_addc_u32 s5, s5, 0
	s_add_u32 s4, s4, s84
	s_addc_u32 s5, s5, 0
	s_add_u32 s18, s4, 0x31400000
	s_addc_u32 s19, s5, 0
	s_lshl_b32 s12, s76, 8
	s_add_i32 s78, s83, 0
	s_bitset1_b32 s84, 13
	s_add_i32 s87, s12, 0
	s_add_i32 s85, s84, 0
	s_add_i32 s86, s78, 0xc000
	s_add_i32 s87, s87, 0x12000
	s_add_u32 s20, s7, 0x2d410000
	s_addc_u32 s21, s10, 0
	s_add_u32 s30, s0, 0x29001000
	s_addc_u32 s31, s1, 0
	s_add_u32 s34, s7, 0x2d420000
	s_addc_u32 s35, s10, 0
	s_add_u32 s36, s0, 0x29002000
	s_addc_u32 s37, s1, 0
	s_add_u32 s38, s7, 0x2d430000
	s_addc_u32 s39, s10, 0
	s_add_u32 s40, s0, 0x29003000
	s_addc_u32 s41, s1, 0
	s_add_u32 s42, s4, 0x31410000
	s_addc_u32 s43, s5, 0
	s_lshl_b32 s6, s6, 7
	s_add_u32 s6, s26, s6
	s_addc_u32 s12, s27, 0
	s_add_u32 s44, s6, 0x29400000
	s_addc_u32 s45, s12, 0
	s_lshl_b32 s13, s76, 12
	s_add_i32 s88, s13, 0
	s_add_i32 s88, s88, 0x12800
	s_add_u32 s46, s6, 0x3b400000
	s_addc_u32 s47, s12, 0
	s_add_u32 s48, s0, 0x29005000
	s_addc_u32 s49, s1, 0
	s_add_u32 s50, s7, 0x2d450000
	s_addc_u32 s51, s10, 0
	s_add_u32 s52, s4, 0x31430000
	s_addc_u32 s53, s5, 0
	s_add_u32 s89, s0, 0x29004000
	s_waitcnt lgkmcnt(1)
	v_mov_b32_e32 v1, 0
	s_mov_b32 s11, 0
	s_addc_u32 s90, s1, 0
	v_mov_b32_e32 v200, s86
	v_mov_b32_e32 v201, s83
	s_add_i32 s91, 0, 0x3000
	v_mov_b32_e32 v202, s84
	v_mov_b32_e32 v16, v1
	v_mov_b32_e32 v17, v1
	v_mov_b32_e32 v18, v1
	v_mov_b32_e32 v19, v1
	v_mov_b32_e32 v20, v1
	v_mov_b32_e32 v21, v1
	v_mov_b32_e32 v22, v1
	v_mov_b32_e32 v23, v1
	v_mov_b32_e32 v24, v1
	v_mov_b32_e32 v25, v1
	v_mov_b32_e32 v26, v1
	v_mov_b32_e32 v27, v1
	v_mov_b32_e32 v28, v1
	v_mov_b32_e32 v29, v1
	v_mov_b32_e32 v30, v1
	v_mov_b32_e32 v31, v1
	s_add_i32 s92, 0, 0x6000
	s_add_i32 s93, 0, 0x9000
	s_mov_b32 s94, 0x41000000
	v_mov_b32_e32 v203, 0xff800000
	s_mov_b32 s0, 0
	s_branch .LBB0_826

.LBB0_908:
	s_setprio 0
	s_waitcnt vmcnt(0) lgkmcnt(0)
	s_barrier
